# layer-1 weight transposes moved from the RMSNorm phase into the idle workgroups of the gate_up GEMM last round
# speedup vs baseline: 1.0003x; 1.0003x over previous
.LBB0_730:
	s_cmpk_gt_i32 s18, 0x81f
	s_branch .LBB0_745

.LBB0_805:
	s_cmp_lt_u32 s2, 128
	s_cbranch_scc1 .Lx1_end
	s_load_dwordx2 s[10:11], s[0:1], 0xe0
	v_mov_b32_e32 v30, v152
	v_and_b32_e32 v29, 63, v30
	v_lshlrev_b32_e32 v20, 3, v29
	v_readfirstlane_b32 s4, v30
	s_ashr_i32 s21, s4, 6
	s_sub_u32 s4, s2, 128
	s_lshl_b32 s4, s4, 3
	s_add_i32 s18, s4, s21
	s_sub_u32 s20, s38, 128
	s_lshl_b32 s19, s20, 3
	s_mov_b32 s8, s0
	s_mov_b32 s9, s1
	s_waitcnt lgkmcnt(0)
	s_cmpk_gt_i32 s18, 0x81f
	s_cbranch_scc1 .Lx1_end
	s_load_dwordx4 s[4:7], s[8:9], 0x18
	s_load_dwordx4 s[24:27], s[8:9], 0xa8
	s_lshl_b32 s8, s21, 14
	v_lshrrev_b32_e32 v18, 5, v29
	v_lshlrev_b32_e32 v0, 2, v30
	s_add_i32 s8, s8, 0
	v_and_b32_e32 v0, 0x7c, v0
	v_mul_u32_u24_e32 v4, 0x84, v18
	v_mov_b32_e32 v1, 0
	v_add3_u32 v19, s8, v0, v4
	v_and_b32_e32 v4, 56, v20
	s_waitcnt lgkmcnt(0)
	v_lshl_add_u64 v[2:3], s[6:7], 0, v[0:1]
	s_mov_b64 s[6:7], 0x400000
	v_lshrrev_b32_e32 v21, 3, v29
	v_mul_u32_u24_e32 v6, 0x84, v4
	v_lshlrev_b32_e32 v4, 1, v4
	v_mov_b32_e32 v5, v1
	v_lshl_add_u64 v[2:3], v[2:3], 0, s[6:7]
	s_waitcnt vmcnt(0)
	v_lshl_add_u64 v[16:17], s[10:11], 0, v[4:5]
	s_mov_b64 s[6:7], 0x1290000
	v_lshlrev_b32_e32 v7, 2, v21
	v_lshl_add_u64 v[4:5], v[16:17], 0, s[6:7]
	v_add3_u32 v20, s8, v6, v7
	v_lshl_add_u64 v[6:7], s[26:27], 0, v[0:1]
	s_mov_b64 s[6:7], 0x100000
	v_lshl_add_u64 v[6:7], v[6:7], 0, s[6:7]
	s_mov_b64 s[6:7], 0x1210000
	v_lshl_add_u64 v[8:9], v[16:17], 0, s[6:7]
	v_lshl_add_u64 v[10:11], s[24:25], 0, v[0:1]
	s_mov_b64 s[6:7], 0x120000
	v_lshl_add_u64 v[14:15], s[4:5], 0, v[0:1]
	s_mov_b64 s[4:5], 0xa20000
	v_lshl_add_u64 v[10:11], v[10:11], 0, s[6:7]
	s_mov_b64 s[6:7], 0x1180000
	v_lshl_add_u64 v[14:15], v[14:15], 0, s[4:5]
	s_mov_b64 s[4:5], 0xc00000
	v_lshl_add_u64 v[12:13], v[16:17], 0, s[6:7]
	v_lshl_add_u64 v[16:17], v[16:17], 0, s[4:5]
	s_lshl_b32 s4, s18, 1
	s_mov_b32 s9, 0
	v_or_b32_e32 v22, 8, v21
	v_or_b32_e32 v23, 16, v21
	v_or_b32_e32 v24, 24, v21
	s_lshl_b32 s6, s18, 5
	s_lshl_b32 s7, s20, 8
	s_add_i32 s10, s4, 0x1f3c0
	s_lshl_b32 s11, s20, 4
	s_movk_i32 s14, 0x4000
	s_movk_i32 s15, 0x6000
	s_mov_b32 s16, 0xa000
	s_mov_b32 s17, 0xc000
	s_mov_b32 s20, 0x10000
	s_mov_b32 s21, 0x12000
	s_mov_b32 s22, 0x16000
	s_mov_b32 s23, 0x18000
	s_mov_b32 s24, 0x1c000
	s_mov_b32 s25, 0x1e000
	s_mov_b32 s26, 0x22000
	s_mov_b32 s27, 0x24000
	s_mov_b32 s28, 0x28000
	s_mov_b32 s29, 0x2a000
	s_mov_b32 s30, 0x2e000
	s_movk_i32 s31, 0x1000
	s_movk_i32 s34, 0x3000
	s_movk_i32 s35, 0x7000
	s_mov_b32 s36, 0x9000
	s_mov_b32 s37, 0xd000
	s_mov_b32 s42, 0xf000
	s_mov_b32 s43, 0x13000
	s_mov_b32 s44, 0x15000
	s_mov_b32 s45, 0x19000
	s_mov_b32 s46, 0x1b000
	s_mov_b32 s47, 0x1f000
	s_mov_b32 s48, 0x21000
	s_mov_b32 s49, 0x25000
	s_mov_b32 s50, 0x27000
	s_mov_b32 s51, 0x2b000
	s_mov_b32 s52, 0x2d000
	s_movk_i32 s53, 0x2880
	v_add_u32_e32 v25, 0x400, v19
	v_add_u32_e32 v26, 0x800, v19
	v_add_u32_e32 v27, 0xc00, v19
	v_add_u32_e32 v28, 0x1000, v19
	v_add_u32_e32 v29, 0x1400, v19
	v_add_u32_e32 v30, 0x1800, v19
	v_add_u32_e32 v31, 0x1c00, v19
	s_branch .Lx1_733

.Lx1_743:
	s_andn2_b64 vcc, exec, s[4:5]
	s_cbranch_vccnz .Lx1_732
	s_mul_hi_i32 s4, s18, 0x1948b0fd
	s_lshr_b32 s5, s4, 31
	s_ashr_i32 s4, s4, 3
	s_add_i32 s4, s4, s5
	s_mul_i32 s8, s4, 0xfffff5e0
	s_mul_i32 s5, s4, 0xffffffaf
	s_add_i32 s40, s6, s8
	s_add_i32 s5, s18, s5
	s_add_i32 s8, s40, 0x80
	s_cmp_lt_i32 s5, 28
	s_cselect_b32 s8, s40, s8
	s_lshl_b32 s4, s4, 6
	v_or_b32_e32 v0, s4, v18
	s_ashr_i32 s41, s40, 31
	v_lshl_add_u64 v[32:33], s[40:41], 2, v[14:15]
	v_or_b32_e32 v36, 2, v0
	v_or_b32_e32 v38, 4, v0
	v_or_b32_e32 v40, 6, v0
	v_or_b32_e32 v42, 8, v0
	v_or_b32_e32 v44, 10, v0
	v_or_b32_e32 v46, 12, v0
	v_or_b32_e32 v48, 14, v0
	v_mad_i64_i32 v[34:35], s[40:41], v0, s53, v[32:33]
	v_mad_i64_i32 v[36:37], s[40:41], v36, s53, v[32:33]
	v_mad_i64_i32 v[38:39], s[40:41], v38, s53, v[32:33]
	v_mad_i64_i32 v[40:41], s[40:41], v40, s53, v[32:33]
	v_mad_i64_i32 v[42:43], s[40:41], v42, s53, v[32:33]
	v_mad_i64_i32 v[44:45], s[40:41], v44, s53, v[32:33]
	v_mad_i64_i32 v[46:47], s[40:41], v46, s53, v[32:33]
	v_mad_i64_i32 v[48:49], s[40:41], v48, s53, v[32:33]
	global_load_dword v50, v[34:35], off
	global_load_dword v51, v[36:37], off
	global_load_dword v52, v[38:39], off
	global_load_dword v53, v[40:41], off
	global_load_dword v54, v[42:43], off
	global_load_dword v55, v[44:45], off
	global_load_dword v56, v[46:47], off
	global_load_dword v57, v[48:49], off
	v_or_b32_e32 v34, 16, v0
	v_or_b32_e32 v36, 18, v0
	v_or_b32_e32 v38, 20, v0
	v_or_b32_e32 v40, 22, v0
	v_or_b32_e32 v42, 24, v0
	v_or_b32_e32 v44, 26, v0
	v_or_b32_e32 v46, 28, v0
	v_or_b32_e32 v48, 30, v0
	v_mad_i64_i32 v[34:35], s[40:41], v34, s53, v[32:33]
	v_mad_i64_i32 v[36:37], s[40:41], v36, s53, v[32:33]
	v_mad_i64_i32 v[38:39], s[40:41], v38, s53, v[32:33]
	v_mad_i64_i32 v[40:41], s[40:41], v40, s53, v[32:33]
	v_mad_i64_i32 v[42:43], s[40:41], v42, s53, v[32:33]
	v_mad_i64_i32 v[44:45], s[40:41], v44, s53, v[32:33]
	v_mad_i64_i32 v[46:47], s[40:41], v46, s53, v[32:33]
	v_mad_i64_i32 v[48:49], s[40:41], v48, s53, v[32:33]
	global_load_dword v58, v[34:35], off
	global_load_dword v59, v[36:37], off
	global_load_dword v60, v[38:39], off
	global_load_dword v61, v[40:41], off
	global_load_dword v62, v[42:43], off
	global_load_dword v63, v[44:45], off
	global_load_dword v64, v[46:47], off
	global_load_dword v65, v[48:49], off
	v_or_b32_e32 v34, 32, v0
	v_or_b32_e32 v36, 34, v0
	v_or_b32_e32 v38, 36, v0
	v_or_b32_e32 v40, 38, v0
	v_or_b32_e32 v42, 40, v0
	v_or_b32_e32 v44, 42, v0
	v_or_b32_e32 v46, 44, v0
	v_or_b32_e32 v48, 46, v0
	v_mad_i64_i32 v[34:35], s[40:41], v34, s53, v[32:33]
	v_mad_i64_i32 v[36:37], s[40:41], v36, s53, v[32:33]
	v_mad_i64_i32 v[38:39], s[40:41], v38, s53, v[32:33]
	v_mad_i64_i32 v[40:41], s[40:41], v40, s53, v[32:33]
	v_mad_i64_i32 v[42:43], s[40:41], v42, s53, v[32:33]
	v_mad_i64_i32 v[44:45], s[40:41], v44, s53, v[32:33]
	v_mad_i64_i32 v[46:47], s[40:41], v46, s53, v[32:33]
	v_mad_i64_i32 v[48:49], s[40:41], v48, s53, v[32:33]
	global_load_dword v66, v[34:35], off
	global_load_dword v67, v[36:37], off
	global_load_dword v68, v[38:39], off
	global_load_dword v69, v[40:41], off
	global_load_dword v70, v[42:43], off
	global_load_dword v71, v[44:45], off
	global_load_dword v72, v[46:47], off
	s_nop 0
	global_load_dword v48, v[48:49], off
	v_or_b32_e32 v34, 48, v0
	v_or_b32_e32 v36, 50, v0
	v_or_b32_e32 v38, 52, v0
	v_or_b32_e32 v40, 54, v0
	v_or_b32_e32 v42, 56, v0
	v_or_b32_e32 v44, 58, v0
	v_or_b32_e32 v46, 60, v0
	v_or_b32_e32 v0, 62, v0
	v_mad_i64_i32 v[34:35], s[40:41], v34, s53, v[32:33]
	v_mad_i64_i32 v[36:37], s[40:41], v36, s53, v[32:33]
	v_mad_i64_i32 v[38:39], s[40:41], v38, s53, v[32:33]
	v_mad_i64_i32 v[40:41], s[40:41], v40, s53, v[32:33]
	v_mad_i64_i32 v[42:43], s[40:41], v42, s53, v[32:33]
	v_mad_i64_i32 v[44:45], s[40:41], v44, s53, v[32:33]
	v_mad_i64_i32 v[46:47], s[40:41], v46, s53, v[32:33]
	v_mad_i64_i32 v[32:33], s[40:41], v0, s53, v[32:33]
	global_load_dword v0, v[34:35], off
	s_nop 0
	global_load_dword v34, v[36:37], off
	global_load_dword v35, v[38:39], off
	s_nop 0
	global_load_dword v36, v[40:41], off
	global_load_dword v37, v[42:43], off
	global_load_dword v38, v[44:45], off
	global_load_dword v39, v[46:47], off
	s_nop 0
	global_load_dword v32, v[32:33], off
	s_waitcnt vmcnt(30)
	ds_write2_b32 v19, v50, v51 offset1:66
	s_waitcnt vmcnt(28)
	ds_write2_b32 v19, v52, v53 offset0:132 offset1:198
	s_waitcnt vmcnt(26)
	ds_write2_b32 v25, v54, v55 offset0:8 offset1:74
	s_waitcnt vmcnt(24)
	ds_write2_b32 v25, v56, v57 offset0:140 offset1:206
	s_waitcnt vmcnt(22)
	ds_write2_b32 v26, v58, v59 offset0:16 offset1:82
	s_waitcnt vmcnt(20)
	ds_write2_b32 v26, v60, v61 offset0:148 offset1:214
	s_waitcnt vmcnt(18)
	ds_write2_b32 v27, v62, v63 offset0:24 offset1:90
	s_waitcnt vmcnt(16)
	ds_write2_b32 v27, v64, v65 offset0:156 offset1:222
	s_waitcnt vmcnt(14)
	ds_write2_b32 v28, v66, v67 offset0:32 offset1:98
	s_waitcnt vmcnt(12)
	ds_write2_b32 v28, v68, v69 offset0:164 offset1:230
	s_waitcnt vmcnt(10)
	ds_write2_b32 v29, v70, v71 offset0:40 offset1:106
	s_waitcnt vmcnt(8)
	ds_write2_b32 v29, v72, v48 offset0:172 offset1:238
	s_waitcnt vmcnt(6)
	ds_write2_b32 v30, v0, v34 offset0:48 offset1:114
	s_waitcnt vmcnt(4)
	ds_write2_b32 v30, v35, v36 offset0:180 offset1:246
	s_waitcnt vmcnt(2)
	ds_write2_b32 v31, v37, v38 offset0:56 offset1:122
	s_waitcnt vmcnt(0)
	ds_write2_b32 v31, v39, v32 offset0:188 offset1:254
	s_waitcnt lgkmcnt(0)
	ds_read2_b32 v[32:33], v20 offset1:33
	s_waitcnt lgkmcnt(0)
	v_cvt_pk_bf16_f32 v32, v32, v33
	ds_read2_b32 v[34:35], v20 offset0:66 offset1:99
	s_waitcnt lgkmcnt(0)
	v_cvt_pk_bf16_f32 v33, v34, v35
	ds_read2_b32 v[34:35], v20 offset0:132 offset1:165
	s_waitcnt lgkmcnt(0)
	v_cvt_pk_bf16_f32 v34, v34, v35
	ds_read2_b32 v[36:37], v20 offset0:198 offset1:231
	s_waitcnt lgkmcnt(0)
	v_cvt_pk_bf16_f32 v35, v36, v37
	v_or_b32_e32 v36, s8, v21
	s_ashr_i32 s5, s4, 31
	v_ashrrev_i32_e32 v37, 31, v36
	v_lshl_add_u64 v[38:39], s[4:5], 1, v[16:17]
	v_lshlrev_b64 v[36:37], 11, v[36:37]
	v_lshl_add_u64 v[36:37], v[38:39], 0, v[36:37]
	ds_read2_b32 v[40:41], v20 offset0:8 offset1:41
	global_store_dwordx4 v[36:37], v[32:35], off
	s_waitcnt lgkmcnt(0)
	s_nop 0
	v_cvt_pk_bf16_f32 v32, v40, v41
	ds_read2_b32 v[34:35], v20 offset0:74 offset1:107
	s_waitcnt lgkmcnt(0)
	v_cvt_pk_bf16_f32 v33, v34, v35
	ds_read2_b32 v[34:35], v20 offset0:140 offset1:173
	s_waitcnt lgkmcnt(0)
	v_cvt_pk_bf16_f32 v34, v34, v35
	ds_read2_b32 v[36:37], v20 offset0:206 offset1:239
	s_waitcnt lgkmcnt(0)
	v_cvt_pk_bf16_f32 v35, v36, v37
	v_or_b32_e32 v36, s8, v22
	v_ashrrev_i32_e32 v37, 31, v36
	v_lshlrev_b64 v[36:37], 11, v[36:37]
	v_lshl_add_u64 v[36:37], v[38:39], 0, v[36:37]
	ds_read2_b32 v[40:41], v20 offset0:16 offset1:49
	global_store_dwordx4 v[36:37], v[32:35], off
	s_waitcnt lgkmcnt(0)
	s_nop 0
	v_cvt_pk_bf16_f32 v32, v40, v41
	ds_read2_b32 v[34:35], v20 offset0:82 offset1:115
	s_waitcnt lgkmcnt(0)
	v_cvt_pk_bf16_f32 v33, v34, v35
	ds_read2_b32 v[34:35], v20 offset0:148 offset1:181
	s_waitcnt lgkmcnt(0)
	v_cvt_pk_bf16_f32 v34, v34, v35
	ds_read2_b32 v[36:37], v20 offset0:214 offset1:247
	s_waitcnt lgkmcnt(0)
	v_cvt_pk_bf16_f32 v35, v36, v37
	v_or_b32_e32 v36, s8, v23
	v_ashrrev_i32_e32 v37, 31, v36
	v_lshlrev_b64 v[36:37], 11, v[36:37]
	v_lshl_add_u64 v[36:37], v[38:39], 0, v[36:37]
	ds_read2_b32 v[40:41], v20 offset0:24 offset1:57
	global_store_dwordx4 v[36:37], v[32:35], off
	s_waitcnt lgkmcnt(0)
	s_nop 0
	v_cvt_pk_bf16_f32 v32, v40, v41
	ds_read2_b32 v[34:35], v20 offset0:90 offset1:123
	s_waitcnt lgkmcnt(0)
	v_cvt_pk_bf16_f32 v33, v34, v35
	ds_read2_b32 v[34:35], v20 offset0:156 offset1:189
	s_waitcnt lgkmcnt(0)
	v_cvt_pk_bf16_f32 v34, v34, v35
	ds_read2_b32 v[36:37], v20 offset0:222 offset1:255
	s_waitcnt lgkmcnt(0)
	v_cvt_pk_bf16_f32 v35, v36, v37
	v_or_b32_e32 v36, s8, v24
	v_ashrrev_i32_e32 v37, 31, v36
	v_lshlrev_b64 v[36:37], 11, v[36:37]
	v_lshl_add_u64 v[36:37], v[38:39], 0, v[36:37]
	global_store_dwordx4 v[36:37], v[32:35], off
	s_waitcnt lgkmcnt(0)
	s_branch .Lx1_732
.Lx1_end:
	s_waitcnt vmcnt(0)
	s_waitcnt vmcnt(0)
	s_barrier
	s_and_saveexec_b64 s[42:43], s[12:13]
	s_cbranch_execz .LBB0_849
	s_add_i32 s4, 0, 0x20020
	v_mov_b32_e32 v0, s4
	s_waitcnt vmcnt(0) expcnt(0) lgkmcnt(0)
	ds_read_b32 v0, v0
	s_add_i32 s4, 0, 0x20024
	v_mov_b32_e32 v1, s4
	ds_read_b32 v2, v1
	s_waitcnt lgkmcnt(1)
	v_cmp_ne_u32_e32 vcc, 0, v0
	s_cbranch_vccnz .LBB0_820
	s_mov_b64 s[4:5], 0x4200
	v_lshl_add_u64 v[0:1], v[128:129], 0, s[4:5]
	s_mov_b64 s[4:5], 0x4400
	s_waitcnt lgkmcnt(0)
	v_lshl_add_u64 v[2:3], v[128:129], 0, s[4:5]
	s_mov_b64 s[4:5], 0x4500
	s_load_dword s6, s[80:81], 0x14
	v_lshl_add_u64 v[4:5], v[128:129], 0, s[4:5]
	s_mov_b64 s[4:5], 0x4600
	v_lshl_add_u64 v[6:7], v[128:129], 0, s[4:5]
	s_mov_b64 s[4:5], 0x4700
	v_lshl_add_u64 v[8:9], v[128:129], 0, s[4:5]
	s_mov_b64 s[4:5], 0x4800
	v_lshl_add_u64 v[10:11], v[128:129], 0, s[4:5]
	s_mov_b64 s[4:5], 0x4900
	v_lshl_add_u64 v[12:13], v[128:129], 0, s[4:5]
	s_mov_b64 s[4:5], 0x4a00
	s_waitcnt lgkmcnt(0)
	s_lshr_b32 s8, s6, 16
	s_and_b32 s6, s6, 0xffff
	v_lshl_add_u64 v[14:15], v[128:129], 0, s[4:5]
	s_mov_b64 s[4:5], 0x4b00
	s_cmp_lg_u32 s6, 0
	v_lshl_add_u64 v[16:17], v[128:129], 0, s[4:5]
	s_mov_b64 s[4:5], 0x4c00
	s_cselect_b64 s[6:7], -1, 0
	v_lshl_add_u64 v[18:19], v[128:129], 0, s[4:5]
	s_mov_b64 s[4:5], 0x4d00
	s_cmp_lg_u64 s[6:7], 0
	v_lshl_add_u64 v[20:21], v[128:129], 0, s[4:5]
	s_mov_b64 s[4:5], 0x4e00
	s_addc_u32 s6, s39, 0
	v_lshl_add_u64 v[22:23], v[128:129], 0, s[4:5]
	s_mov_b64 s[4:5], 0x4f00
	s_cmp_lg_u32 s8, 0
	v_lshl_add_u64 v[24:25], v[128:129], 0, s[4:5]
	s_mov_b64 s[4:5], 0x5000
	s_mul_i32 s24, s6, s38
	s_cselect_b64 s[6:7], -1, 0
	v_lshl_add_u64 v[26:27], v[128:129], 0, s[4:5]
	s_mov_b64 s[4:5], 0x5100
	s_cmp_lg_u64 s[6:7], 0
	v_lshl_add_u64 v[28:29], v[128:129], 0, s[4:5]
	s_mov_b64 s[4:5], 0x5200
	s_addc_u32 s6, s78, 0
	v_lshl_add_u64 v[30:31], v[128:129], 0, s[4:5]
	s_mov_b64 s[4:5], 0x5300
	s_mul_i32 s24, s24, s6
	v_lshl_add_u64 v[32:33], v[128:129], 0, s[4:5]
	s_mov_b32 s25, 1
	s_mov_b64 s[4:5], 0
	s_branch .LBB0_810
